# placement check: post-P0 instruction stream shifted by +48 bytes
# speedup vs baseline: 1.0019x; 1.0019x over previous
; __global__ void __launch_bounds__(512, 2) fwd_megakernel(Args args) {
;     ...
;     float* MOD = (float*)(ws + WS_MOD); float* CTXS = (float*)(ws + WS_CTXS);
;     bf16_t* W256 = (bf16_t*)(ws + WS_W256); bf16_t* CS256 = (bf16_t*)(ws + WS_CS256); float* AT = (float*)(ws + WS_AT);
;     bf16_t* WINT = (bf16_t*)(ws + WS_WINT); bf16_t* WOUTT = (bf16_t*)(ws + WS_WOUTT); bf16_t* WGLUT = (bf16_t*)(ws + WS_WGLUT); bf16_t* WFT = (bf16_t*)(ws + WS_WFT);
;     bf16_t* W13T = (bf16_t*)(ws + WS_W13T); bf16_t* W2T = (bf16_t*)(ws + WS_W2T); bf16_t* TC = (bf16_t*)(ws + WS_TC); bf16_t* BS = (bf16_t*)(ws + WS_BS);
;     ...
;         const Ctx X = mkctx(lds);
;         float* scr = (float*)(lds + X.wave * 16384);
;         constexpr int I13 = 16 * 88, I2 = 44 * 32, IIN = 16 * 40, IO = 16 * 32, IG = 8 * 16;
;         constexpr int NITEMS = 8 * I13 + 4 * I2 + IIN + IO + IG + IO;
;         const bool ssmblk = X.G >= 64 && X.bx >= X.G - 32;
;         const int GW = X.G >= 64 ? X.G - 32 : X.G;
;         if (!ssmblk) {
;         for (int it = X.gw; it < NITEMS; it += GW * 8) {
;             int r = it;
;             if (r < 8 * I13) { const int which = r / (4 * I13); r %= 4 * I13; const int lh = r / I13; r %= I13;
;                 if (which == 0) tr_item<1>(args.in[7] + (size_t)lh * D * FF, D, FF, W13T + (size_t)lh * NUP * D, scr, r, X.lane);
;                 else tr_item<2>(args.in[8] + (size_t)lh * D * FF, D, FF, W13T + (size_t)lh * NUP * D, scr, r, X.lane);
;                 continue; }
;             r -= 8 * I13;
;             if (r < 4 * I2) { const int lh = r / I2; r %= I2; tr_item<0>(args.in[9] + (size_t)lh * FF * D, FF, D, W2T + (size_t)lh * D * FF, scr, r, X.lane); continue; }
;             r -= 4 * I2;
;             if (r < IIN) { tr_item<0>(args.in[10], D, INW, WINT, scr, r, X.lane); continue; } r -= IIN;
;             if (r < IO) { tr_item<0>(args.in[23], D, D, WOUTT, scr, r, X.lane); continue; } r -= IO;
;             if (r < IG) { tr_item<0>(args.in[22], 512, 512, WGLUT, scr, r, X.lane); continue; } r -= IG;
;             tr_item<0>(args.in[24], D, D, WFT, scr, r, X.lane);
;         }
.LBB0_6:
	s_nop 0
	s_nop 0
	s_nop 0
	s_nop 0
	s_nop 0
	s_nop 0
	s_nop 0
	s_nop 0
	s_nop 0
	s_nop 0
	s_nop 0
	s_nop 0
	s_load_dwordx16 s[36:51], s[0:1], 0x0
	s_add_u32 s0, s88, 0xa00000
	v_writelane_b32 v254, s8, 2
	s_addc_u32 s1, s89, 0
	s_add_u32 s96, s88, 0xb00000
	v_writelane_b32 v254, s9, 3
	v_writelane_b32 v254, s0, 4
	s_addc_u32 s97, s89, 0
	v_mov_b32_e32 v112, v206
	v_writelane_b32 v254, s1, 5
	s_add_u32 s0, s88, 0xe00000
	s_addc_u32 s1, s89, 0
	v_writelane_b32 v254, s0, 6
	s_nop 0
	v_readfirstlane_b32 s3, v112
	v_writelane_b32 v254, s1, 7
	s_add_u32 s0, s88, 0x1000000
	s_addc_u32 s1, s89, 0
	v_writelane_b32 v254, s0, 8
	v_and_b32_e32 v2, 63, v112
	s_nop 0
	v_writelane_b32 v254, s1, 9
	s_add_u32 s0, s88, 0x1100000
	s_addc_u32 s1, s89, 0
	s_add_u32 s95, s88, 0x1300000
	v_writelane_b32 v254, s0, 10
	s_addc_u32 s30, s89, 0
	s_nop 0
	v_writelane_b32 v254, s1, 11
	s_add_u32 s0, s88, 0x3f00000
	v_writelane_b32 v254, s0, 12
	s_addc_u32 s0, s89, 0
	v_writelane_b32 v254, s0, 13
	s_lshl_b32 s0, s2, 3
	s_cmp_gt_i32 s90, 63
	s_cselect_b64 s[12:13], -1, 0
	s_sub_i32 s18, s90, 32
	s_cmp_ge_i32 s2, s18
	v_writelane_b32 v254, s0, 14
	s_cselect_b64 s[0:1], -1, 0
	s_and_b64 s[0:1], s[12:13], s[0:1]
	s_ashr_i32 s28, s3, 6
	s_andn2_b64 vcc, exec, s[0:1]
	s_mov_b64 s[0:1], -1
	v_writelane_b32 v254, s93, 15
	s_cbranch_vccz .LBB0_54
	v_writelane_b32 v254, s12, 16
	s_and_b64 s[0:1], s[12:13], exec
	s_mov_b32 s0, s18
	v_writelane_b32 v254, s13, 17
	v_writelane_b32 v254, s0, 18
	s_cselect_b32 s3, s18, s90
	s_nop 0
	v_writelane_b32 v254, s1, 19
	s_nop 0
	v_readlane_b32 s0, v254, 14
	s_add_i32 s13, s28, s0
	s_cmpk_gt_i32 s13, 0x48ff
	s_cbranch_scc1 .LBB0_33
	v_lshlrev_b32_e32 v10, 3, v2
	s_lshl_b32 s0, s28, 14
	v_lshrrev_b32_e32 v1, 5, v2
	v_and_b32_e32 v4, 31, v112
	v_lshrrev_b32_e32 v5, 3, v2
	v_and_b32_e32 v10, 56, v10
	s_add_i32 s0, s0, 0
	v_lshlrev_b32_e32 v6, 2, v4
	v_mul_u32_u24_e32 v3, 0x84, v1
	v_mul_u32_u24_e32 v14, 0x84, v10
	v_lshlrev_b32_e32 v26, 2, v5
	v_mov_b32_e32 v7, 0
	v_add3_u32 v3, s0, v3, v6
	v_add3_u32 v30, s0, v14, v26
	v_readlane_b32 s0, v254, 8
	v_lshlrev_b32_e32 v24, 1, v10
	v_mov_b32_e32 v25, v7
	v_readlane_b32 s1, v254, 9
	v_and_b32_e32 v11, 16, v26
	v_readlane_b32 s4, v254, 10
	v_lshl_add_u64 v[16:17], s[0:1], 0, v[24:25]
	v_readlane_b32 s0, v254, 6
	v_readlane_b32 s1, v254, 7
	v_readlane_b32 s5, v254, 11
	v_or_b32_e32 v31, v5, v26
	v_lshl_add_u64 v[20:21], s[0:1], 0, v[24:25]
	s_lshl_b32 s0, s2, 4
	s_lshl_b32 s1, s28, 1
	s_add_i32 s0, s0, s1
	v_or_b32_e32 v32, v11, v5
	s_add_i32 s15, s0, 0x17200
	s_lshl_b32 s0, s2, 5
	s_lshl_b32 s1, s28, 2
	s_lshl_b32 s14, s3, 3
	v_lshl_add_u64 v[8:9], s[84:85], 0, v[6:7]
	v_lshl_add_u64 v[12:13], s[4:5], 0, v[24:25]
	v_lshl_add_u64 v[14:15], s[80:81], 0, v[6:7]
	v_lshl_add_u64 v[18:19], s[82:83], 0, v[6:7]
	v_lshl_add_u64 v[22:23], s[56:57], 0, v[6:7]
	v_lshl_add_u64 v[24:25], s[96:97], 0, v[24:25]
	v_bitop3_b32 v33, v5, 19, v26 bitop3:0xc8
	v_or_b32_e32 v34, 0x8c, v26
	v_or_b32_e32 v35, 12, v26
	v_or_b32_e32 v36, 4, v32
	v_or_b32_e32 v37, 12, v31
	s_lshl_b32 s16, s3, 4
	s_add_i32 s17, s0, s1
	s_lshl_b32 s18, s3, 5
	s_movk_i32 s94, 0x2000
	s_movk_i32 s93, 0x4000
	s_mov_b32 s26, 0x10000
	s_mov_b32 s31, 0x16000
	v_add_u32_e32 v38, 0x400, v3
	v_add_u32_e32 v39, 0x800, v3
	v_add_u32_e32 v40, 0xc00, v3
	v_add_u32_e32 v41, 0x1000, v3
	v_add_u32_e32 v42, 0x1400, v3
	v_add_u32_e32 v43, 0x1800, v3
	v_add_u32_e32 v44, 0x1c00, v3
	v_mov_b32_e32 v45, 0x2000
	v_mov_b32_e32 v46, 0x6000
	v_mov_b32_e32 v47, 0x200
	v_mov_b32_e32 v48, 0x1000
	v_mov_b32_e32 v49, 0x3000
	v_mov_b32_e32 v50, 0x63
	s_mov_b32 s83, 0x26000
	s_mov_b32 s21, 0x2c000
	s_mov_b32 s27, 0x3c000
	s_movk_i32 s57, 0x5000
	s_mov_b32 s80, 0xb000
	s_mov_b32 s10, 0x1b000
	s_mov_b32 s11, 0x37000
	s_mov_b32 s82, 0x4d000
	s_mov_b32 s19, 0x6e000
	s_mov_b32 s12, 0x73000
	s_mov_b32 s20, 0x79000
	s_mov_b32 s84, 0x7e000
	s_mov_b32 s85, 0x84000
	s_mov_b32 s22, 0x89000
	s_mov_b32 s25, 0x8f000
	s_mov_b32 s56, 0x94000
	s_mov_b32 s23, 0x9a000
	s_mov_b32 s24, 0x9f000
	s_mov_b32 s29, 0xa5000
	s_mov_b32 s81, 0xaa000
	s_mov_b32 s1, 0
	s_branch .LBB0_10
